# RG-LRU pass B gate/decay stage regenerated like pass A (single accumulator buffer, MFMAs of the next channel group issued after the last accumulator read)
# speedup vs baseline: 1.0045x; 1.0021x over previous
.LBB0_274:
	v_add_co_u32_e32 v120, vcc, 0x1200b000, v120
	v_lshl_add_u64 v[122:123], v[190:191], 0, v[166:167]
	s_nop 0
	v_addc_co_u32_e32 v121, vcc, 0, v121, vcc
	global_load_dwordx4 v[124:127], v[122:123], off
	s_add_i32 s20, s20, -1
	global_load_dwordx4 v[120:123], v[120:121], off
	s_waitcnt lgkmcnt(0)
	ds_read_b128 v[128:131], v229 offset:11008
	v_lshl_add_u64 v[180:181], v[180:181], 0, s[62:63]
	v_lshl_add_u64 v[190:191], v[190:191], 0, s[62:63]
	s_cmp_lg_u32 s20, 0
	s_waitcnt lgkmcnt(0)
	v_lshlrev_b32_e32 v132, 16, v128
	v_and_b32_e32 v133, 0xffff0000, v128
	v_lshlrev_b32_e32 v128, 16, v129
	v_and_b32_e32 v129, 0xffff0000, v129
	v_lshlrev_b32_e32 v134, 16, v130
	v_and_b32_e32 v135, 0xffff0000, v130
	v_lshlrev_b32_e32 v130, 16, v131
	v_and_b32_e32 v131, 0xffff0000, v131
	v_pk_fma_f32 v[136:137], v[6:7], v[128:129], v[22:23]
	v_pk_fma_f32 v[138:139], v[2:3], v[130:131], v[18:19]
	ds_read_b128 v[128:131], v229 offset:11152
	v_pk_fma_f32 v[132:133], v[4:5], v[132:133], v[20:21]
	v_pk_fma_f32 v[134:135], v[0:1], v[134:135], v[16:17]
	s_waitcnt lgkmcnt(0)
	v_lshlrev_b32_e32 v140, 16, v128
	v_and_b32_e32 v141, 0xffff0000, v128
	v_lshlrev_b32_e32 v128, 16, v129
	v_and_b32_e32 v129, 0xffff0000, v129
	v_lshlrev_b32_e32 v142, 16, v130
	v_and_b32_e32 v143, 0xffff0000, v130
	v_lshlrev_b32_e32 v130, 16, v131
	v_and_b32_e32 v131, 0xffff0000, v131
	v_pk_fma_f32 v[136:137], v[14:15], v[128:129], v[136:137]
	v_pk_fma_f32 v[138:139], v[10:11], v[130:131], v[138:139]
	ds_read_b128 v[128:131], v229 offset:11296
	v_pk_fma_f32 v[132:133], v[12:13], v[140:141], v[132:133]
	v_pk_fma_f32 v[134:135], v[8:9], v[142:143], v[134:135]
	s_waitcnt lgkmcnt(0)
	v_lshlrev_b32_e32 v140, 16, v128
	v_and_b32_e32 v141, 0xffff0000, v128
	v_lshlrev_b32_e32 v128, 16, v129
	v_and_b32_e32 v129, 0xffff0000, v129
	v_lshlrev_b32_e32 v142, 16, v130
	v_and_b32_e32 v143, 0xffff0000, v130
	v_lshlrev_b32_e32 v130, 16, v131
	v_and_b32_e32 v131, 0xffff0000, v131
	v_pk_fma_f32 v[132:133], v[24:25], v[140:141], v[132:133]
	v_pk_fma_f32 v[136:137], v[26:27], v[128:129], v[136:137]
	v_pk_fma_f32 v[140:141], v[28:29], v[142:143], v[134:135]
	v_pk_fma_f32 v[134:135], v[30:31], v[130:131], v[138:139]
	ds_read_b128 v[128:131], v229 offset:11440
	s_waitcnt lgkmcnt(0)
	v_lshlrev_b32_e32 v138, 16, v128
	v_and_b32_e32 v139, 0xffff0000, v128
	v_lshlrev_b32_e32 v128, 16, v129
	v_and_b32_e32 v129, 0xffff0000, v129
	v_lshlrev_b32_e32 v142, 16, v130
	v_and_b32_e32 v143, 0xffff0000, v130
	v_lshlrev_b32_e32 v144, 16, v131
	v_and_b32_e32 v145, 0xffff0000, v131
	v_pk_fma_f32 v[130:131], v[34:35], v[128:129], v[136:137]
	v_pk_fma_f32 v[128:129], v[32:33], v[138:139], v[132:133]
	v_pk_fma_f32 v[134:135], v[38:39], v[144:145], v[134:135]
	v_pk_fma_f32 v[132:133], v[36:37], v[142:143], v[140:141]
	ds_write_b128 v228, v[128:131] offset:2304
	ds_write_b128 v228, v[132:135] offset:2320
	v_cvt_pk_bf16_f32 v128, v128, v129
	v_cvt_pk_bf16_f32 v129, v130, v131
	v_cvt_pk_bf16_f32 v130, v132, v133
	v_cvt_pk_bf16_f32 v131, v134, v135
	ds_write_b128 v229, v[128:131]
	ds_read_b128 v[128:131], v229 offset:12160
	s_waitcnt lgkmcnt(0)
	v_lshlrev_b32_e32 v132, 16, v128
	v_and_b32_e32 v133, 0xffff0000, v128
	v_lshlrev_b32_e32 v128, 16, v129
	v_and_b32_e32 v129, 0xffff0000, v129
	v_lshlrev_b32_e32 v134, 16, v130
	v_and_b32_e32 v135, 0xffff0000, v130
	v_lshlrev_b32_e32 v130, 16, v131
	v_and_b32_e32 v131, 0xffff0000, v131
	v_pk_fma_f32 v[136:137], v[6:7], v[128:129], v[22:23]
	v_pk_fma_f32 v[138:139], v[2:3], v[130:131], v[18:19]
	ds_read_b128 v[128:131], v229 offset:12304
	v_pk_fma_f32 v[132:133], v[4:5], v[132:133], v[20:21]
	v_pk_fma_f32 v[134:135], v[0:1], v[134:135], v[16:17]
	s_waitcnt lgkmcnt(0)
	v_lshlrev_b32_e32 v140, 16, v128
	v_and_b32_e32 v141, 0xffff0000, v128
	v_lshlrev_b32_e32 v128, 16, v129
	v_and_b32_e32 v129, 0xffff0000, v129
	v_lshlrev_b32_e32 v142, 16, v130
	v_and_b32_e32 v143, 0xffff0000, v130
	v_lshlrev_b32_e32 v130, 16, v131
	v_and_b32_e32 v131, 0xffff0000, v131
	v_pk_fma_f32 v[136:137], v[14:15], v[128:129], v[136:137]
	v_pk_fma_f32 v[138:139], v[10:11], v[130:131], v[138:139]
	ds_read_b128 v[128:131], v229 offset:12448
	v_pk_fma_f32 v[132:133], v[12:13], v[140:141], v[132:133]
	v_pk_fma_f32 v[134:135], v[8:9], v[142:143], v[134:135]
	s_waitcnt lgkmcnt(0)
	v_lshlrev_b32_e32 v140, 16, v128
	v_and_b32_e32 v141, 0xffff0000, v128
	v_lshlrev_b32_e32 v128, 16, v129
	v_and_b32_e32 v129, 0xffff0000, v129
	v_lshlrev_b32_e32 v142, 16, v130
	v_and_b32_e32 v143, 0xffff0000, v130
	v_lshlrev_b32_e32 v130, 16, v131
	v_and_b32_e32 v131, 0xffff0000, v131
	v_pk_fma_f32 v[132:133], v[24:25], v[140:141], v[132:133]
	v_pk_fma_f32 v[136:137], v[26:27], v[128:129], v[136:137]
	v_pk_fma_f32 v[140:141], v[28:29], v[142:143], v[134:135]
	v_pk_fma_f32 v[134:135], v[30:31], v[130:131], v[138:139]
	ds_read_b128 v[128:131], v229 offset:12592
	s_waitcnt lgkmcnt(0)
	v_lshlrev_b32_e32 v138, 16, v128
	v_and_b32_e32 v139, 0xffff0000, v128
	v_lshlrev_b32_e32 v128, 16, v129
	v_and_b32_e32 v129, 0xffff0000, v129
	v_lshlrev_b32_e32 v142, 16, v130
	v_and_b32_e32 v143, 0xffff0000, v130
	v_lshlrev_b32_e32 v144, 16, v131
	v_and_b32_e32 v145, 0xffff0000, v131
	v_pk_fma_f32 v[130:131], v[34:35], v[128:129], v[136:137]
	v_pk_fma_f32 v[128:129], v[32:33], v[138:139], v[132:133]
	v_pk_fma_f32 v[134:135], v[38:39], v[144:145], v[134:135]
	v_pk_fma_f32 v[132:133], v[36:37], v[142:143], v[140:141]
	ds_write_b128 v228, v[128:131] offset:4480
	ds_write_b128 v228, v[132:135] offset:4496
	v_cvt_pk_bf16_f32 v128, v128, v129
	v_cvt_pk_bf16_f32 v129, v130, v131
	v_cvt_pk_bf16_f32 v130, v132, v133
	v_cvt_pk_bf16_f32 v131, v134, v135
	ds_write_b128 v229, v[128:131] offset:1152
	s_waitcnt lgkmcnt(0)
	s_mov_b32 s0, 0x37d00d01
	s_mov_b32 s1, 0x37d00d01
	s_mov_b32 s26, 0x3ab60b61
	s_mov_b32 s27, 0x3ab60b61
	s_mov_b32 s72, 0x3c088889
	s_mov_b32 s73, 0x3c088889
	ds_read_b128 v[128:131], v222
	ds_read_b128 v[240:243], v222 offset:64
	v_mov_b32_e32 v248, 1.0
	v_mov_b32_e32 v250, 0xbfb8aa3b
	v_add_u32_e32 v249, 2304, v223
	s_waitcnt lgkmcnt(0)
	v_mfma_f32_16x16x32_bf16 v[144:147], v[128:131], v[40:43], 0
	v_mfma_f32_16x16x32_bf16 v[148:151], v[128:131], v[72:75], 0
	v_mfma_f32_16x16x32_bf16 v[144:147], v[240:243], v[44:47], v[144:147]
	v_mfma_f32_16x16x32_bf16 v[148:151], v[240:243], v[76:79], v[148:151]
	s_nop 7
	s_nop 7
	s_nop 7
	ds_read2_b32 v[246:247], v249 offset0:0 offset1:68
	v_add_f32_e64 v132, v144, v173
	v_add_f32_e64 v133, v145, v173
	v_add_f32_e64 v140, v148, v175
	v_add_f32_e64 v141, v149, v175
	v_pk_mul_f32 v[132:133], v[132:133], v[250:251] op_sel_hi:[1,0]
	v_pk_mul_f32 v[140:141], v[140:141], v[250:251] op_sel_hi:[1,0]
	v_exp_f32_e32 v132, v132
	v_exp_f32_e32 v133, v133
	v_exp_f32_e32 v140, v140
	v_exp_f32_e32 v141, v141
	v_pk_add_f32 v[132:133], v[132:133], v[248:249] op_sel_hi:[1,0]
	v_pk_add_f32 v[140:141], v[140:141], v[248:249] op_sel_hi:[1,0]
	v_rcp_f32_e32 v132, v132
	v_rcp_f32_e32 v133, v133
	v_rcp_f32_e32 v140, v140
	v_rcp_f32_e32 v141, v141
	v_pk_mul_f32 v[142:143], v[132:133], v[236:237] op_sel_hi:[1,0]
	v_mul_f32_e32 v192, 0x3fb8aa3b, v142
	v_mul_f32_e32 v193, 0x3fb8aa3b, v143
	v_pk_add_f32 v[142:143], v[142:143], v[142:143]
	v_exp_f32_e32 v192, v192
	v_exp_f32_e32 v193, v193
	v_pk_fma_f32 v[244:245], v[142:143], s[0:1], v[198:199] op_sel_hi:[1,1,0]
	v_pk_fma_f32 v[244:245], v[142:143], v[244:245], s[26:27]
	v_pk_fma_f32 v[244:245], v[142:143], v[244:245], s[72:73]
	v_fmaak_f32 v244, v142, v244, 0x3d2aaaab
	v_fmaak_f32 v245, v143, v245, 0x3d2aaaab
	v_fmaak_f32 v244, v142, v244, 0x3e2aaaab
	v_fmaak_f32 v245, v143, v245, 0x3e2aaaab
	v_fma_f32 v244, v142, v244, 0.5
	v_fma_f32 v245, v143, v245, 0.5
	v_pk_fma_f32 v[244:245], v[142:143], v[244:245], v[248:249] op_sel_hi:[1,1,0]
	v_pk_mul_f32 v[244:245], v[142:143], v[244:245] neg_lo:[0,1] neg_hi:[0,1]
	v_max_f32_e32 v244, 0, v244
	v_max_f32_e32 v245, 0, v245
	v_sqrt_f32_e32 v244, v244
	v_sqrt_f32_e32 v245, v245
	ds_write_b32 v223, v192 offset:6656
	ds_write_b32 v223, v193 offset:6928
	v_pk_mul_f32 v[244:245], v[140:141], v[244:245]
	s_waitcnt lgkmcnt(2)
	v_pk_mul_f32 v[244:245], v[246:247], v[244:245]
	ds_write2_b32 v249, v244, v245 offset0:0 offset1:68
	ds_read2_b32 v[246:247], v249 offset0:136 offset1:204
	v_add_f32_e64 v132, v146, v173
	v_add_f32_e64 v133, v147, v173
	v_add_f32_e64 v140, v150, v175
	v_add_f32_e64 v141, v151, v175
	v_mfma_f32_16x16x32_bf16 v[144:147], v[128:131], v[48:51], 0
	v_mfma_f32_16x16x32_bf16 v[148:151], v[128:131], v[80:83], 0
	v_mfma_f32_16x16x32_bf16 v[144:147], v[240:243], v[52:55], v[144:147]
	v_mfma_f32_16x16x32_bf16 v[148:151], v[240:243], v[84:87], v[148:151]
	v_pk_mul_f32 v[132:133], v[132:133], v[250:251] op_sel_hi:[1,0]
	v_pk_mul_f32 v[140:141], v[140:141], v[250:251] op_sel_hi:[1,0]
	v_exp_f32_e32 v132, v132
	v_exp_f32_e32 v133, v133
	v_exp_f32_e32 v140, v140
	v_exp_f32_e32 v141, v141
	v_pk_add_f32 v[132:133], v[132:133], v[248:249] op_sel_hi:[1,0]
	v_pk_add_f32 v[140:141], v[140:141], v[248:249] op_sel_hi:[1,0]
	v_rcp_f32_e32 v132, v132
	v_rcp_f32_e32 v133, v133
	v_rcp_f32_e32 v140, v140
	v_rcp_f32_e32 v141, v141
	v_pk_mul_f32 v[142:143], v[132:133], v[236:237] op_sel_hi:[1,0]
	v_mul_f32_e32 v192, 0x3fb8aa3b, v142
	v_mul_f32_e32 v193, 0x3fb8aa3b, v143
	v_pk_add_f32 v[142:143], v[142:143], v[142:143]
	v_exp_f32_e32 v192, v192
	v_exp_f32_e32 v193, v193
	v_pk_fma_f32 v[244:245], v[142:143], s[0:1], v[198:199] op_sel_hi:[1,1,0]
	v_pk_fma_f32 v[244:245], v[142:143], v[244:245], s[26:27]
	v_pk_fma_f32 v[244:245], v[142:143], v[244:245], s[72:73]
	v_fmaak_f32 v244, v142, v244, 0x3d2aaaab
	v_fmaak_f32 v245, v143, v245, 0x3d2aaaab
	v_fmaak_f32 v244, v142, v244, 0x3e2aaaab
	v_fmaak_f32 v245, v143, v245, 0x3e2aaaab
	v_fma_f32 v244, v142, v244, 0.5
	v_fma_f32 v245, v143, v245, 0.5
	v_pk_fma_f32 v[244:245], v[142:143], v[244:245], v[248:249] op_sel_hi:[1,1,0]
	v_pk_mul_f32 v[244:245], v[142:143], v[244:245] neg_lo:[0,1] neg_hi:[0,1]
	v_max_f32_e32 v244, 0, v244
	v_max_f32_e32 v245, 0, v245
	v_sqrt_f32_e32 v244, v244
	v_sqrt_f32_e32 v245, v245
	ds_write_b32 v223, v192 offset:7200
	ds_write_b32 v223, v193 offset:7472
	v_pk_mul_f32 v[244:245], v[140:141], v[244:245]
	s_waitcnt lgkmcnt(2)
	v_pk_mul_f32 v[244:245], v[246:247], v[244:245]
	ds_write2_b32 v249, v244, v245 offset0:136 offset1:204
	ds_read2_b32 v[246:247], v249 offset0:16 offset1:84
	v_pk_add_f32 v[132:133], v[144:145], v[230:231] op_sel_hi:[1,0]
	v_add_f32_e64 v140, v148, v231
	v_add_f32_e64 v141, v149, v231
	v_pk_mul_f32 v[132:133], v[132:133], v[250:251] op_sel_hi:[1,0]
	v_pk_mul_f32 v[140:141], v[140:141], v[250:251] op_sel_hi:[1,0]
	v_exp_f32_e32 v132, v132
	v_exp_f32_e32 v133, v133
	v_exp_f32_e32 v140, v140
	v_exp_f32_e32 v141, v141
	v_pk_add_f32 v[132:133], v[132:133], v[248:249] op_sel_hi:[1,0]
	v_pk_add_f32 v[140:141], v[140:141], v[248:249] op_sel_hi:[1,0]
	v_rcp_f32_e32 v132, v132
	v_rcp_f32_e32 v133, v133
	v_rcp_f32_e32 v140, v140
	v_rcp_f32_e32 v141, v141
	v_mul_f32_e64 v142, v132, v237
	v_mul_f32_e64 v143, v133, v237
	v_mul_f32_e32 v192, 0x3fb8aa3b, v142
	v_mul_f32_e32 v193, 0x3fb8aa3b, v143
	v_pk_add_f32 v[142:143], v[142:143], v[142:143]
	v_exp_f32_e32 v192, v192
	v_exp_f32_e32 v193, v193
	v_pk_fma_f32 v[244:245], v[142:143], s[0:1], v[198:199] op_sel_hi:[1,1,0]
	v_pk_fma_f32 v[244:245], v[142:143], v[244:245], s[26:27]
	v_pk_fma_f32 v[244:245], v[142:143], v[244:245], s[72:73]
	v_fmaak_f32 v244, v142, v244, 0x3d2aaaab
	v_fmaak_f32 v245, v143, v245, 0x3d2aaaab
	v_fmaak_f32 v244, v142, v244, 0x3e2aaaab
	v_fmaak_f32 v245, v143, v245, 0x3e2aaaab
	v_fma_f32 v244, v142, v244, 0.5
	v_fma_f32 v245, v143, v245, 0.5
	v_pk_fma_f32 v[244:245], v[142:143], v[244:245], v[248:249] op_sel_hi:[1,1,0]
	v_pk_mul_f32 v[244:245], v[142:143], v[244:245] neg_lo:[0,1] neg_hi:[0,1]
	v_max_f32_e32 v244, 0, v244
	v_max_f32_e32 v245, 0, v245
	v_sqrt_f32_e32 v244, v244
	v_sqrt_f32_e32 v245, v245
	ds_write_b32 v223, v192 offset:6720
	ds_write_b32 v223, v193 offset:6992
	v_pk_mul_f32 v[244:245], v[140:141], v[244:245]
	s_waitcnt lgkmcnt(2)
	v_pk_mul_f32 v[244:245], v[246:247], v[244:245]
	ds_write2_b32 v249, v244, v245 offset0:16 offset1:84
	ds_read2_b32 v[246:247], v249 offset0:152 offset1:220
	v_pk_add_f32 v[132:133], v[146:147], v[230:231] op_sel_hi:[1,0]
	v_add_f32_e64 v140, v150, v231
	v_add_f32_e64 v141, v151, v231
	v_mfma_f32_16x16x32_bf16 v[144:147], v[128:131], v[56:59], 0
	v_mfma_f32_16x16x32_bf16 v[148:151], v[128:131], v[88:91], 0
	v_mfma_f32_16x16x32_bf16 v[144:147], v[240:243], v[60:63], v[144:147]
	v_mfma_f32_16x16x32_bf16 v[148:151], v[240:243], v[92:95], v[148:151]
	v_pk_mul_f32 v[132:133], v[132:133], v[250:251] op_sel_hi:[1,0]
	v_pk_mul_f32 v[140:141], v[140:141], v[250:251] op_sel_hi:[1,0]
	v_exp_f32_e32 v132, v132
	v_exp_f32_e32 v133, v133
	v_exp_f32_e32 v140, v140
	v_exp_f32_e32 v141, v141
	v_pk_add_f32 v[132:133], v[132:133], v[248:249] op_sel_hi:[1,0]
	v_pk_add_f32 v[140:141], v[140:141], v[248:249] op_sel_hi:[1,0]
	v_rcp_f32_e32 v132, v132
	v_rcp_f32_e32 v133, v133
	v_rcp_f32_e32 v140, v140
	v_rcp_f32_e32 v141, v141
	v_mul_f32_e64 v142, v132, v237
	v_mul_f32_e64 v143, v133, v237
	v_mul_f32_e32 v192, 0x3fb8aa3b, v142
	v_mul_f32_e32 v193, 0x3fb8aa3b, v143
	v_pk_add_f32 v[142:143], v[142:143], v[142:143]
	v_exp_f32_e32 v192, v192
	v_exp_f32_e32 v193, v193
	v_pk_fma_f32 v[244:245], v[142:143], s[0:1], v[198:199] op_sel_hi:[1,1,0]
	v_pk_fma_f32 v[244:245], v[142:143], v[244:245], s[26:27]
	v_pk_fma_f32 v[244:245], v[142:143], v[244:245], s[72:73]
	v_fmaak_f32 v244, v142, v244, 0x3d2aaaab
	v_fmaak_f32 v245, v143, v245, 0x3d2aaaab
	v_fmaak_f32 v244, v142, v244, 0x3e2aaaab
	v_fmaak_f32 v245, v143, v245, 0x3e2aaaab
	v_fma_f32 v244, v142, v244, 0.5
	v_fma_f32 v245, v143, v245, 0.5
	v_pk_fma_f32 v[244:245], v[142:143], v[244:245], v[248:249] op_sel_hi:[1,1,0]
	v_pk_mul_f32 v[244:245], v[142:143], v[244:245] neg_lo:[0,1] neg_hi:[0,1]
	v_max_f32_e32 v244, 0, v244
	v_max_f32_e32 v245, 0, v245
	v_sqrt_f32_e32 v244, v244
	v_sqrt_f32_e32 v245, v245
	ds_write_b32 v223, v192 offset:7264
	ds_write_b32 v223, v193 offset:7536
	v_pk_mul_f32 v[244:245], v[140:141], v[244:245]
	s_waitcnt lgkmcnt(2)
	v_pk_mul_f32 v[244:245], v[246:247], v[244:245]
	ds_write2_b32 v249, v244, v245 offset0:152 offset1:220
	ds_read2_b32 v[246:247], v249 offset0:32 offset1:100
	v_pk_add_f32 v[132:133], v[144:145], v[232:233] op_sel_hi:[1,0]
	v_add_f32_e64 v140, v148, v233
	v_add_f32_e64 v141, v149, v233
	v_pk_mul_f32 v[132:133], v[132:133], v[250:251] op_sel_hi:[1,0]
	v_pk_mul_f32 v[140:141], v[140:141], v[250:251] op_sel_hi:[1,0]
	v_exp_f32_e32 v132, v132
	v_exp_f32_e32 v133, v133
	v_exp_f32_e32 v140, v140
	v_exp_f32_e32 v141, v141
	v_pk_add_f32 v[132:133], v[132:133], v[248:249] op_sel_hi:[1,0]
	v_pk_add_f32 v[140:141], v[140:141], v[248:249] op_sel_hi:[1,0]
	v_rcp_f32_e32 v132, v132
	v_rcp_f32_e32 v133, v133
	v_rcp_f32_e32 v140, v140
	v_rcp_f32_e32 v141, v141
	v_pk_mul_f32 v[142:143], v[132:133], v[238:239] op_sel_hi:[1,0]
	v_mul_f32_e32 v192, 0x3fb8aa3b, v142
	v_mul_f32_e32 v193, 0x3fb8aa3b, v143
	v_pk_add_f32 v[142:143], v[142:143], v[142:143]
	v_exp_f32_e32 v192, v192
	v_exp_f32_e32 v193, v193
	v_pk_fma_f32 v[244:245], v[142:143], s[0:1], v[198:199] op_sel_hi:[1,1,0]
	v_pk_fma_f32 v[244:245], v[142:143], v[244:245], s[26:27]
	v_pk_fma_f32 v[244:245], v[142:143], v[244:245], s[72:73]
	v_fmaak_f32 v244, v142, v244, 0x3d2aaaab
	v_fmaak_f32 v245, v143, v245, 0x3d2aaaab
	v_fmaak_f32 v244, v142, v244, 0x3e2aaaab
	v_fmaak_f32 v245, v143, v245, 0x3e2aaaab
	v_fma_f32 v244, v142, v244, 0.5
	v_fma_f32 v245, v143, v245, 0.5
	v_pk_fma_f32 v[244:245], v[142:143], v[244:245], v[248:249] op_sel_hi:[1,1,0]
	v_pk_mul_f32 v[244:245], v[142:143], v[244:245] neg_lo:[0,1] neg_hi:[0,1]
	v_max_f32_e32 v244, 0, v244
	v_max_f32_e32 v245, 0, v245
	v_sqrt_f32_e32 v244, v244
	v_sqrt_f32_e32 v245, v245
	ds_write_b32 v223, v192 offset:6784
	ds_write_b32 v223, v193 offset:7056
	v_pk_mul_f32 v[244:245], v[140:141], v[244:245]
	s_waitcnt lgkmcnt(2)
	v_pk_mul_f32 v[244:245], v[246:247], v[244:245]
	ds_write2_b32 v249, v244, v245 offset0:32 offset1:100
	ds_read2_b32 v[246:247], v249 offset0:168 offset1:236
	v_pk_add_f32 v[132:133], v[146:147], v[232:233] op_sel_hi:[1,0]
	v_add_f32_e64 v140, v150, v233
	v_add_f32_e64 v141, v151, v233
	v_mfma_f32_16x16x32_bf16 v[144:147], v[128:131], v[64:67], 0
	v_mfma_f32_16x16x32_bf16 v[148:151], v[128:131], v[100:103], 0
	v_mfma_f32_16x16x32_bf16 v[144:147], v[240:243], v[68:71], v[144:147]
	v_mfma_f32_16x16x32_bf16 v[148:151], v[240:243], v[104:107], v[148:151]
	v_pk_mul_f32 v[132:133], v[132:133], v[250:251] op_sel_hi:[1,0]
	v_pk_mul_f32 v[140:141], v[140:141], v[250:251] op_sel_hi:[1,0]
	v_exp_f32_e32 v132, v132
	v_exp_f32_e32 v133, v133
	v_exp_f32_e32 v140, v140
	v_exp_f32_e32 v141, v141
	v_pk_add_f32 v[132:133], v[132:133], v[248:249] op_sel_hi:[1,0]
	v_pk_add_f32 v[140:141], v[140:141], v[248:249] op_sel_hi:[1,0]
	v_rcp_f32_e32 v132, v132
	v_rcp_f32_e32 v133, v133
	v_rcp_f32_e32 v140, v140
	v_rcp_f32_e32 v141, v141
	v_pk_mul_f32 v[142:143], v[132:133], v[238:239] op_sel_hi:[1,0]
	v_mul_f32_e32 v192, 0x3fb8aa3b, v142
	v_mul_f32_e32 v193, 0x3fb8aa3b, v143
	v_pk_add_f32 v[142:143], v[142:143], v[142:143]
	v_exp_f32_e32 v192, v192
	v_exp_f32_e32 v193, v193
	v_pk_fma_f32 v[244:245], v[142:143], s[0:1], v[198:199] op_sel_hi:[1,1,0]
	v_pk_fma_f32 v[244:245], v[142:143], v[244:245], s[26:27]
	v_pk_fma_f32 v[244:245], v[142:143], v[244:245], s[72:73]
	v_fmaak_f32 v244, v142, v244, 0x3d2aaaab
	v_fmaak_f32 v245, v143, v245, 0x3d2aaaab
	v_fmaak_f32 v244, v142, v244, 0x3e2aaaab
	v_fmaak_f32 v245, v143, v245, 0x3e2aaaab
	v_fma_f32 v244, v142, v244, 0.5
	v_fma_f32 v245, v143, v245, 0.5
	v_pk_fma_f32 v[244:245], v[142:143], v[244:245], v[248:249] op_sel_hi:[1,1,0]
	v_pk_mul_f32 v[244:245], v[142:143], v[244:245] neg_lo:[0,1] neg_hi:[0,1]
	v_max_f32_e32 v244, 0, v244
	v_max_f32_e32 v245, 0, v245
	v_sqrt_f32_e32 v244, v244
	v_sqrt_f32_e32 v245, v245
	ds_write_b32 v223, v192 offset:7328
	ds_write_b32 v223, v193 offset:7600
	v_pk_mul_f32 v[244:245], v[140:141], v[244:245]
	s_waitcnt lgkmcnt(2)
	v_pk_mul_f32 v[244:245], v[246:247], v[244:245]
	ds_write2_b32 v249, v244, v245 offset0:168 offset1:236
	ds_read2_b32 v[246:247], v249 offset0:48 offset1:116
	v_add_f32_e64 v132, v144, v235
	v_add_f32_e64 v133, v145, v235
	v_pk_add_f32 v[140:141], v[148:149], v[234:235] op_sel_hi:[1,0]
	v_pk_mul_f32 v[132:133], v[132:133], v[250:251] op_sel_hi:[1,0]
	v_pk_mul_f32 v[140:141], v[140:141], v[250:251] op_sel_hi:[1,0]
	v_exp_f32_e32 v132, v132
	v_exp_f32_e32 v133, v133
	v_exp_f32_e32 v140, v140
	v_exp_f32_e32 v141, v141
	v_pk_add_f32 v[132:133], v[132:133], v[248:249] op_sel_hi:[1,0]
	v_pk_add_f32 v[140:141], v[140:141], v[248:249] op_sel_hi:[1,0]
	v_rcp_f32_e32 v132, v132
	v_rcp_f32_e32 v133, v133
	v_rcp_f32_e32 v140, v140
	v_rcp_f32_e32 v141, v141
	v_mul_f32_e64 v142, v132, v239
	v_mul_f32_e64 v143, v133, v239
	v_mul_f32_e32 v192, 0x3fb8aa3b, v142
	v_mul_f32_e32 v193, 0x3fb8aa3b, v143
	v_pk_add_f32 v[142:143], v[142:143], v[142:143]
	v_exp_f32_e32 v192, v192
	v_exp_f32_e32 v193, v193
	v_pk_fma_f32 v[244:245], v[142:143], s[0:1], v[198:199] op_sel_hi:[1,1,0]
	v_pk_fma_f32 v[244:245], v[142:143], v[244:245], s[26:27]
	v_pk_fma_f32 v[244:245], v[142:143], v[244:245], s[72:73]
	v_fmaak_f32 v244, v142, v244, 0x3d2aaaab
	v_fmaak_f32 v245, v143, v245, 0x3d2aaaab
	v_fmaak_f32 v244, v142, v244, 0x3e2aaaab
	v_fmaak_f32 v245, v143, v245, 0x3e2aaaab
	v_fma_f32 v244, v142, v244, 0.5
	v_fma_f32 v245, v143, v245, 0.5
	v_pk_fma_f32 v[244:245], v[142:143], v[244:245], v[248:249] op_sel_hi:[1,1,0]
	v_pk_mul_f32 v[244:245], v[142:143], v[244:245] neg_lo:[0,1] neg_hi:[0,1]
	v_max_f32_e32 v244, 0, v244
	v_max_f32_e32 v245, 0, v245
	v_sqrt_f32_e32 v244, v244
	v_sqrt_f32_e32 v245, v245
	ds_write_b32 v223, v192 offset:6848
	ds_write_b32 v223, v193 offset:7120
	v_pk_mul_f32 v[244:245], v[140:141], v[244:245]
	s_waitcnt lgkmcnt(2)
	v_pk_mul_f32 v[244:245], v[246:247], v[244:245]
	ds_write2_b32 v249, v244, v245 offset0:48 offset1:116
	ds_read2_b32 v[246:247], v249 offset0:184 offset1:252
	v_add_f32_e64 v132, v146, v235
	v_add_f32_e64 v133, v147, v235
	v_pk_add_f32 v[140:141], v[150:151], v[234:235] op_sel_hi:[1,0]
	v_pk_mul_f32 v[132:133], v[132:133], v[250:251] op_sel_hi:[1,0]
	v_pk_mul_f32 v[140:141], v[140:141], v[250:251] op_sel_hi:[1,0]
	v_exp_f32_e32 v132, v132
	v_exp_f32_e32 v133, v133
	v_exp_f32_e32 v140, v140
	v_exp_f32_e32 v141, v141
	v_pk_add_f32 v[132:133], v[132:133], v[248:249] op_sel_hi:[1,0]
	v_pk_add_f32 v[140:141], v[140:141], v[248:249] op_sel_hi:[1,0]
	v_rcp_f32_e32 v132, v132
	v_rcp_f32_e32 v133, v133
	v_rcp_f32_e32 v140, v140
	v_rcp_f32_e32 v141, v141
	v_mul_f32_e64 v142, v132, v239
	v_mul_f32_e64 v143, v133, v239
	v_mul_f32_e32 v192, 0x3fb8aa3b, v142
	v_mul_f32_e32 v193, 0x3fb8aa3b, v143
	v_pk_add_f32 v[142:143], v[142:143], v[142:143]
	v_exp_f32_e32 v192, v192
	v_exp_f32_e32 v193, v193
	v_pk_fma_f32 v[244:245], v[142:143], s[0:1], v[198:199] op_sel_hi:[1,1,0]
	v_pk_fma_f32 v[244:245], v[142:143], v[244:245], s[26:27]
	v_pk_fma_f32 v[244:245], v[142:143], v[244:245], s[72:73]
	v_fmaak_f32 v244, v142, v244, 0x3d2aaaab
	v_fmaak_f32 v245, v143, v245, 0x3d2aaaab
	v_fmaak_f32 v244, v142, v244, 0x3e2aaaab
	v_fmaak_f32 v245, v143, v245, 0x3e2aaaab
	v_fma_f32 v244, v142, v244, 0.5
	v_fma_f32 v245, v143, v245, 0.5
	v_pk_fma_f32 v[244:245], v[142:143], v[244:245], v[248:249] op_sel_hi:[1,1,0]
	v_pk_mul_f32 v[244:245], v[142:143], v[244:245] neg_lo:[0,1] neg_hi:[0,1]
	v_max_f32_e32 v244, 0, v244
	v_max_f32_e32 v245, 0, v245
	v_sqrt_f32_e32 v244, v244
	v_sqrt_f32_e32 v245, v245
	ds_write_b32 v223, v192 offset:7392
	ds_write_b32 v223, v193 offset:7664
	v_pk_mul_f32 v[244:245], v[140:141], v[244:245]
	s_waitcnt lgkmcnt(2)
	v_pk_mul_f32 v[244:245], v[246:247], v[244:245]
	ds_write2_b32 v249, v244, v245 offset0:184 offset1:252
	s_waitcnt vmcnt(1)
	v_lshlrev_b32_e32 v139, 16, v127
	v_and_b32_e32 v127, 0xffff0000, v127
	v_lshlrev_b32_e32 v137, 16, v125
	v_and_b32_e32 v125, 0xffff0000, v125
	v_lshlrev_b32_e32 v138, 16, v126
	v_and_b32_e32 v126, 0xffff0000, v126
	v_add_u32_e32 v134, 0xa00, v227
	s_waitcnt lgkmcnt(0)
	v_add_u32_e32 v128, 0x1800, v227
	v_add_u32_e32 v132, 0x800, v227
	ds_read2_b32 v[128:129], v128 offset0:128 offset1:196
	ds_read2_b32 v[130:131], v132 offset0:64 offset1:132
	v_lshlrev_b32_e32 v136, 16, v124
	v_mul_f32_e32 v140, 0x3d372713, v136
	v_mul_f32_e32 v140, v140, v136
	v_and_b32_e32 v124, 0xffff0000, v124
	s_waitcnt lgkmcnt(0)
	v_fma_f32 v128, v177, v128, v130
	v_fmac_f32_e32 v131, v128, v129
	v_add_u32_e32 v130, 0x1c00, v227
	ds_write2_b32 v132, v128, v131 offset0:64 offset1:132
	ds_read2_b32 v[128:129], v130 offset0:8 offset1:76
	ds_read2_b32 v[132:133], v134 offset0:72 offset1:140
	s_waitcnt lgkmcnt(0)
	v_fma_f32 v128, v131, v128, v132
	v_fmac_f32_e32 v133, v128, v129
	v_add_u32_e32 v132, 0xc00, v227
	ds_write2_b32 v134, v128, v133 offset0:72 offset1:140
	ds_read2_b32 v[128:129], v130 offset0:144 offset1:212
	ds_read2_b32 v[130:131], v132 offset0:80 offset1:148
	v_add_u32_e32 v134, 0xe00, v227
	s_waitcnt lgkmcnt(0)
	v_fma_f32 v128, v133, v128, v130
	v_fmac_f32_e32 v131, v128, v129
	v_add_u32_e32 v130, 0x2000, v227
	ds_write2_b32 v132, v128, v131 offset0:80 offset1:148
	ds_read2_b32 v[128:129], v130 offset0:24 offset1:92
	ds_read2_b32 v[132:133], v134 offset0:88 offset1:156
	s_waitcnt lgkmcnt(0)
	v_fma_f32 v128, v131, v128, v132
	v_fmac_f32_e32 v133, v128, v129
	v_add_u32_e32 v132, 0x1000, v227
	ds_write2_b32 v134, v128, v133 offset0:88 offset1:156
	ds_read2_b32 v[128:129], v130 offset0:160 offset1:228
	ds_read2_b32 v[130:131], v132 offset0:96 offset1:164
	v_add_u32_e32 v134, 0x1200, v227
	s_waitcnt lgkmcnt(0)
	v_fma_f32 v128, v133, v128, v130
	v_fmac_f32_e32 v131, v128, v129
	v_add_u32_e32 v130, 0x2400, v227
	ds_write2_b32 v132, v128, v131 offset0:96 offset1:164
	ds_read2_b32 v[128:129], v130 offset0:40 offset1:108
	ds_read2_b32 v[132:133], v134 offset0:104 offset1:172
	s_waitcnt lgkmcnt(0)
	v_fma_f32 v128, v131, v128, v132
	v_fmac_f32_e32 v133, v128, v129
	v_add_u32_e32 v132, 0x1400, v227
	ds_write2_b32 v134, v128, v133 offset0:104 offset1:172
	ds_read2_b32 v[128:129], v130 offset0:176 offset1:244
	ds_read2_b32 v[130:131], v132 offset0:112 offset1:180
	s_waitcnt lgkmcnt(0)
	v_fma_f32 v128, v133, v128, v130
	v_fmac_f32_e32 v131, v128, v129
	ds_write2_b32 v132, v128, v131 offset0:112 offset1:180
	v_add_u32_e32 v128, 0x2800, v227
	v_add_u32_e32 v130, 0x1600, v227
	ds_read2_b32 v[128:129], v128 offset0:56 offset1:124
	ds_read2_b32 v[176:177], v130 offset0:120 offset1:188
	s_waitcnt lgkmcnt(0)
	v_fma_f32 v128, v131, v128, v176
	v_fmac_f32_e32 v177, v128, v129
	ds_write2_b32 v130, v128, v177 offset0:120 offset1:188
	s_waitcnt lgkmcnt(0)
	ds_read_b128 v[128:131], v228 offset:2304
	ds_read_b128 v[132:135], v228 offset:2320
	s_waitcnt lgkmcnt(1)
	v_mul_f32_e32 v128, v128, v136
	v_fmac_f32_e32 v136, v140, v136
	v_mul_f32_e32 v136, 0x3fcc422a, v136
	v_mul_f32_e32 v136, 0xbfb8aa3b, v136
	v_exp_f32_e32 v136, v136
	v_mul_f32_e32 v129, v129, v124
	v_add_f32_e32 v136, 1.0, v136
	v_rcp_f32_e32 v136, v136
	s_nop 0
	v_mul_f32_e32 v128, v136, v128
	v_mul_f32_e32 v136, 0x3d372713, v124
	v_mul_f32_e32 v136, v136, v124
	v_fmac_f32_e32 v124, v136, v124
	v_mul_f32_e32 v124, 0x3fcc422a, v124
	v_mul_f32_e32 v124, 0xbfb8aa3b, v124
	v_exp_f32_e32 v124, v124
	s_nop 0
	v_add_f32_e32 v124, 1.0, v124
	v_rcp_f32_e32 v124, v124
	s_nop 0
	v_mul_f32_e32 v124, v124, v129
	v_mul_f32_e32 v129, v130, v137
	v_mul_f32_e32 v130, 0x3d372713, v137
	v_mul_f32_e32 v130, v130, v137
	v_fmac_f32_e32 v137, v130, v137
	v_mul_f32_e32 v130, 0x3fcc422a, v137
	v_mul_f32_e32 v130, 0xbfb8aa3b, v130
	v_exp_f32_e32 v130, v130
	v_cvt_pk_bf16_f32 v124, v128, v124
	s_nop 0
	v_add_f32_e32 v130, 1.0, v130
	v_rcp_f32_e32 v130, v130
	s_nop 0
	v_mul_f32_e32 v129, v130, v129
	v_mul_f32_e32 v130, v131, v125
	v_mul_f32_e32 v131, 0x3d372713, v125
	v_mul_f32_e32 v131, v131, v125
	v_fmac_f32_e32 v125, v131, v125
	v_mul_f32_e32 v125, 0x3fcc422a, v125
	v_mul_f32_e32 v125, 0xbfb8aa3b, v125
	v_exp_f32_e32 v125, v125
	v_mul_f32_e32 v131, 0x3d372713, v138
	v_mul_f32_e32 v131, v131, v138
	v_add_f32_e32 v125, 1.0, v125
	v_rcp_f32_e32 v125, v125
	s_nop 0
	v_mul_f32_e32 v125, v125, v130
	s_waitcnt lgkmcnt(0)
	v_mul_f32_e32 v130, v132, v138
	v_fmac_f32_e32 v138, v131, v138
	v_mul_f32_e32 v131, 0x3fcc422a, v138
	v_mul_f32_e32 v131, 0xbfb8aa3b, v131
	v_exp_f32_e32 v131, v131
	v_mul_f32_e32 v132, 0x3d372713, v126
	v_mul_f32_e32 v132, v132, v126
	v_cvt_pk_bf16_f32 v125, v129, v125
	v_add_f32_e32 v131, 1.0, v131
	v_rcp_f32_e32 v131, v131
	v_lshl_add_u64 v[128:129], v[188:189], 0, v[166:167]
	v_lshl_add_u64 v[188:189], v[188:189], 0, s[60:61]
	v_mul_f32_e32 v130, v131, v130
	v_mul_f32_e32 v131, v133, v126
	v_fmac_f32_e32 v126, v132, v126
	v_mul_f32_e32 v126, 0x3fcc422a, v126
	v_mul_f32_e32 v126, 0xbfb8aa3b, v126
	v_exp_f32_e32 v126, v126
	v_mul_f32_e32 v132, 0x3d372713, v139
	v_mul_f32_e32 v132, v132, v139
	v_mul_f32_e32 v133, 0x3d372713, v127
	v_add_f32_e32 v126, 1.0, v126
	v_rcp_f32_e32 v126, v126
	v_mul_f32_e32 v133, v133, v127
	v_mul_f32_e32 v126, v126, v131
	v_mul_f32_e32 v131, v134, v139
	v_fmac_f32_e32 v139, v132, v139
	v_mul_f32_e32 v132, 0x3fcc422a, v139
	v_mul_f32_e32 v132, 0xbfb8aa3b, v132
	v_exp_f32_e32 v132, v132
	v_cvt_pk_bf16_f32 v126, v130, v126
	s_waitcnt vmcnt(0)
	v_lshlrev_b32_e32 v134, 16, v122
	v_and_b32_e32 v122, 0xffff0000, v122
	v_add_f32_e32 v132, 1.0, v132
	v_rcp_f32_e32 v132, v132
	s_nop 0
	v_mul_f32_e32 v131, v132, v131
	v_mul_f32_e32 v132, v135, v127
	v_fmac_f32_e32 v127, v133, v127
	v_mul_f32_e32 v127, 0x3fcc422a, v127
	v_mul_f32_e32 v127, 0xbfb8aa3b, v127
	v_exp_f32_e32 v127, v127
	v_lshlrev_b32_e32 v133, 16, v121
	v_and_b32_e32 v121, 0xffff0000, v121
	v_lshlrev_b32_e32 v135, 16, v123
	v_add_f32_e32 v127, 1.0, v127
	v_rcp_f32_e32 v127, v127
	v_and_b32_e32 v123, 0xffff0000, v123
	v_mul_f32_e32 v127, v127, v132
	v_cvt_pk_bf16_f32 v127, v131, v127
	global_store_dwordx4 v[128:129], v[124:127], off
	ds_read_b128 v[124:127], v228 offset:4480
	ds_read_b128 v[128:131], v228 offset:4496
	v_lshlrev_b32_e32 v132, 16, v120
	v_mul_f32_e32 v136, 0x3d372713, v132
	v_mul_f32_e32 v136, v136, v132
	s_waitcnt lgkmcnt(1)
	v_mul_f32_e32 v124, v124, v132
	v_fmac_f32_e32 v132, v136, v132
	v_mul_f32_e32 v132, 0x3fcc422a, v132
	v_mul_f32_e32 v132, 0xbfb8aa3b, v132
	v_exp_f32_e32 v132, v132
	v_and_b32_e32 v120, 0xffff0000, v120
	v_mul_f32_e32 v125, v125, v120
	v_add_f32_e32 v132, 1.0, v132
	v_rcp_f32_e32 v132, v132
	s_nop 0
	v_mul_f32_e32 v124, v132, v124
	v_mul_f32_e32 v132, 0x3d372713, v120
	v_mul_f32_e32 v132, v132, v120
	v_fmac_f32_e32 v120, v132, v120
	v_mul_f32_e32 v120, 0x3fcc422a, v120
	v_mul_f32_e32 v120, 0xbfb8aa3b, v120
	v_exp_f32_e32 v120, v120
	s_nop 0
	v_add_f32_e32 v120, 1.0, v120
	v_rcp_f32_e32 v120, v120
	s_nop 0
	v_mul_f32_e32 v120, v120, v125
	v_mul_f32_e32 v125, v126, v133
	v_mul_f32_e32 v126, 0x3d372713, v133
	v_mul_f32_e32 v126, v126, v133
	v_fmac_f32_e32 v133, v126, v133
	v_mul_f32_e32 v126, 0x3fcc422a, v133
	v_mul_f32_e32 v126, 0xbfb8aa3b, v126
	v_exp_f32_e32 v126, v126
	v_cvt_pk_bf16_f32 v120, v124, v120
	s_nop 0
	v_add_f32_e32 v126, 1.0, v126
	v_rcp_f32_e32 v126, v126
	s_nop 0
	v_mul_f32_e32 v125, v126, v125
	v_mul_f32_e32 v126, v127, v121
	v_mul_f32_e32 v127, 0x3d372713, v121
	v_mul_f32_e32 v127, v127, v121
	v_fmac_f32_e32 v121, v127, v121
	v_mul_f32_e32 v121, 0x3fcc422a, v121
	v_mul_f32_e32 v121, 0xbfb8aa3b, v121
	v_exp_f32_e32 v121, v121
	v_mul_f32_e32 v127, 0x3d372713, v134
	v_mul_f32_e32 v127, v127, v134
	v_add_f32_e32 v121, 1.0, v121
	v_rcp_f32_e32 v121, v121
	s_nop 0
	v_mul_f32_e32 v121, v121, v126
	s_waitcnt lgkmcnt(0)
	v_mul_f32_e32 v126, v128, v134
	v_fmac_f32_e32 v134, v127, v134
	v_mul_f32_e32 v127, 0x3fcc422a, v134
	v_mul_f32_e32 v127, 0xbfb8aa3b, v127
	v_exp_f32_e32 v127, v127
	v_mul_f32_e32 v128, 0x3d372713, v122
	v_mul_f32_e32 v128, v128, v122
	v_cvt_pk_bf16_f32 v121, v125, v121
	v_add_f32_e32 v127, 1.0, v127
	v_rcp_f32_e32 v127, v127
	v_lshl_add_u64 v[124:125], v[178:179], 0, v[166:167]
	v_lshl_add_u64 v[178:179], v[178:179], 0, s[60:61]
	v_mul_f32_e32 v126, v127, v126
	v_mul_f32_e32 v127, v129, v122
	v_fmac_f32_e32 v122, v128, v122
	v_mul_f32_e32 v122, 0x3fcc422a, v122
	v_mul_f32_e32 v122, 0xbfb8aa3b, v122
	v_exp_f32_e32 v122, v122
	v_mul_f32_e32 v128, 0x3d372713, v135
	v_mul_f32_e32 v128, v128, v135
	v_mul_f32_e32 v129, 0x3d372713, v123
	v_add_f32_e32 v122, 1.0, v122
	v_rcp_f32_e32 v122, v122
	v_mul_f32_e32 v129, v129, v123
	v_mul_f32_e32 v122, v122, v127
	v_mul_f32_e32 v127, v130, v135
	v_fmac_f32_e32 v135, v128, v135
	v_mul_f32_e32 v128, 0x3fcc422a, v135
	v_mul_f32_e32 v128, 0xbfb8aa3b, v128
	v_exp_f32_e32 v128, v128
	v_cvt_pk_bf16_f32 v122, v126, v122
	s_nop 0
	v_add_f32_e32 v128, 1.0, v128
	v_rcp_f32_e32 v128, v128
	s_nop 0
	v_mul_f32_e32 v127, v128, v127
	v_mul_f32_e32 v128, v131, v123
	v_fmac_f32_e32 v123, v129, v123
	v_mul_f32_e32 v123, 0x3fcc422a, v123
	v_mul_f32_e32 v123, 0xbfb8aa3b, v123
	v_exp_f32_e32 v123, v123
	s_nop 0
	v_add_f32_e32 v123, 1.0, v123
	v_rcp_f32_e32 v123, v123
	s_nop 0
	v_mul_f32_e32 v123, v123, v128
	v_cvt_pk_bf16_f32 v123, v127, v123
	global_store_dwordx4 v[124:125], v[120:123], off
	s_waitcnt lgkmcnt(0)
	s_cbranch_scc0 .LBB0_249
